# scan loader y reduce reads its four 16-byte partial blocks in lane-rotated order (no 4-way LDS bank conflict on the 64-byte lane stride)
# speedup vs baseline: 1.0080x; 1.0080x over previous
.LBB0_1102:
	v_ashrrev_i32_e32 v45, 31, v44
	v_lshlrev_b64 v[26:27], 1, v[44:45]
	v_or_b32_e32 v26, s37, v26
	v_readlane_b32 s2, v252, 0
	v_readlane_b32 s4, v252, 6
	v_or_b32_e32 v43, s61, v90
	v_sub_u32_e32 v46, s27, v90
	v_lshlrev_b64 v[30:31], 10, v[26:27]
	v_readlane_b32 s3, v252, 1
	v_lshlrev_b64 v[26:27], 9, v[26:27]
	v_readlane_b32 s5, v252, 7
	v_cndmask_b32_e64 v46, v46, v43, s[16:17]
	v_lshl_add_u64 v[28:29], s[2:3], 0, v[30:31]
	v_lshl_add_u64 v[26:27], s[4:5], 0, v[26:27]
	v_mov_b32_e32 v41, v1
	v_ashrrev_i32_e32 v47, 31, v46
	v_readlane_b32 s8, v252, 10
	v_lshl_add_u64 v[28:29], v[28:29], 0, v[0:1]
	v_lshl_add_u64 v[32:33], v[26:27], 0, v[40:41]
	v_readlane_b32 s10, v252, 20
	v_readlane_b32 s12, v252, 22
	v_readlane_b32 s6, v252, 8
	v_lshlrev_b64 v[46:47], 9, v[46:47]
	v_readlane_b32 s9, v252, 11
	v_add_u32_e32 v124, 0x1b800, v123
	s_nop 0
	v_readfirstlane_b32 s98, v124
	s_mov_b32 m0, s98
	s_nop 0
	global_load_lds_dwordx4 v[28:29], off
	s_nop 0
	global_load_dwordx2 v[82:83], v[32:33], off
	v_lshlrev_b64 v[32:33], 10, v[44:45]
	v_readlane_b32 s11, v252, 21
	v_readlane_b32 s13, v252, 23
	v_lshlrev_b64 v[44:45], 9, v[44:45]
	v_readlane_b32 s7, v252, 9
	v_lshl_add_u64 v[46:47], s[8:9], 0, v[46:47]
	s_mov_b32 s27, s21
	v_lshl_add_u64 v[32:33], s[10:11], 0, v[32:33]
	v_lshl_add_u64 v[30:31], s[12:13], 0, v[30:31]
	v_lshl_add_u64 v[44:45], s[6:7], 0, v[44:45]
	v_lshl_add_u64 v[46:47], v[46:47], 0, s[26:27]
	s_mov_b32 s49, s21
	v_lshl_add_u64 v[32:33], v[32:33], 0, v[0:1]
	v_lshl_add_u64 v[34:35], v[30:31], 0, v[0:1]
	v_lshl_add_u64 v[44:45], v[44:45], 0, v[40:41]
	v_lshl_add_u64 v[46:47], v[46:47], 0, s[48:49]
	v_mov_b32_e32 v43, v1
	v_add_u32_e32 v124, 0x1c800, v123
	s_nop 0
	v_readfirstlane_b32 s98, v124
	s_mov_b32 m0, s98
	s_nop 0
	global_load_lds_dwordx4 v[32:33], off
	s_nop 0
	v_add_u32_e32 v124, 0x1d800, v123
	s_nop 0
	v_readfirstlane_b32 s98, v124
	s_mov_b32 m0, s98
	s_nop 0
	global_load_lds_dwordx4 v[34:35], off
	v_lshl_add_u64 v[46:47], v[46:47], 0, v[42:43]
	global_load_dwordx2 v[84:85], v[44:45], off
	global_load_dwordx2 v[86:87], v[46:47], off
	s_lshl_b32 s20, s37, 10
	v_lshl_add_u64 v[60:61], s[2:3], 0, v[0:1]
	s_add_u32 s2, s8, s26
	s_addc_u32 s3, s9, 0
	s_add_u32 s26, s2, s48
	s_addc_u32 s27, s3, 0
	v_readlane_b32 s2, v252, 14
	v_readlane_b32 s3, v252, 15
	s_add_u32 s2, s2, s20
	s_addc_u32 s3, s3, 0
	s_lshl_b32 s48, s60, 2
	s_add_u32 s2, s2, s48
	s_addc_u32 s3, s3, 0
	s_lshl_b32 s50, s33, 2
	s_waitcnt vmcnt(12)
	s_waitcnt lgkmcnt(0)
	s_barrier
	v_lshl_add_u64 v[70:71], s[26:27], 0, v[42:43]
	s_add_u32 s26, s2, s50
	v_lshl_add_u64 v[64:65], s[10:11], 0, v[0:1]
	v_lshl_add_u64 v[66:67], s[12:13], 0, v[0:1]
	v_lshlrev_b32_e32 v0, 6, v39
	v_lshrrev_b32_e32 v94, 2, v39
	s_addc_u32 s27, s3, 0
	v_mov_b32_e32 v39, v1
	v_lshl_add_u64 v[62:63], s[4:5], 0, v[40:41]
	v_lshl_add_u64 v[68:69], s[6:7], 0, v[40:41]
	v_and_b32_e32 v93, 0xc0, v0
	v_add_u32_e32 v0, 0, v0
	v_lshl_add_u64 v[72:73], s[26:27], 0, v[38:39]
	s_sub_i32 s98, 1, s37
	s_sub_i32 s98, s98, s37
	s_ashr_i32 s99, s98, 31
	v_mov_b32_e32 v112, s98
	v_mov_b32_e32 v113, s99
	s_cmp_eq_u32 s37, 0
	s_cselect_b32 s98, 64, 0xbf
	s_add_i32 s98, s98, s25
	v_mov_b32_e32 v110, s98
	v_mad_i32_i24 v111, v55, v112, v110
	v_and_b32_e32 v108, 63, v232
	v_lshrrev_b32_e32 v108, 2, v108
	v_mad_i32_i24 v109, v108, v112, v110
	v_lshl_or_b32 v108, v111, 1, s37
	s_movk_i32 s98, 0x400
	s_movk_i32 s99, 0x200
	v_mad_u64_u32 v[96:97], vcc, v108, s98, v[60:61]
	v_mad_u64_u32 v[98:99], vcc, v108, s99, v[62:63]
	v_mad_u64_u32 v[100:101], vcc, v111, s98, v[64:65]
	v_mad_u64_u32 v[102:103], vcc, v108, s98, v[66:67]
	v_mad_u64_u32 v[104:105], vcc, v111, s99, v[68:69]
	v_mad_u64_u32 v[106:107], vcc, v109, s99, v[70:71]
	s_cmp_eq_u32 s37, 0
	s_cselect_b32 s98, 0, 0xff
	s_add_i32 s98, s98, s25
	v_mov_b32_e32 v110, s98
	v_mad_i32_i24 v111, v55, v112, v110
	s_movk_i32 s98, 0x800
	v_mad_u64_u32 v[108:109], vcc, v111, s98, v[72:73]
	v_and_b32_e32 v126, 0xff, v232
	v_lshrrev_b32_e32 v127, 6, v126
	v_and_b32_e32 v128, 3, v126
	v_lshl_add_u32 v127, v127, 2, v128
	v_lshrrev_b32_e32 v128, 4, v126
	v_sub_u32_e32 v127, v127, v128
	v_mul_i32_i24_e32 v127, v127, v112
	v_lshlrev_b32_e32 v127, 11, v127
	v_bfe_u32 v128, v126, 2, 4
	v_and_b32_e32 v129, 15, v126
	v_sub_u32_e32 v128, v128, v129
	v_lshl_add_u32 v128, v128, 2, v127
	v_ashrrev_i32_e32 v129, 31, v128
	v_lshl_add_u64 v[108:109], v[128:129], 0, v[108:109]
	v_and_b32_e32 v125, 0xff, v232
	v_lshrrev_b32_e32 v130, 2, v125
	v_add_u32_e32 v126, 0, v130
	v_and_b32_e32 v126, 3, v126
	v_lshlrev_b32_e32 v126, 4, v126
	v_lshl_add_u32 v126, v125, 6, v126
	v_add_u32_e32 v127, 1, v130
	v_and_b32_e32 v127, 3, v127
	v_lshlrev_b32_e32 v127, 4, v127
	v_lshl_add_u32 v127, v125, 6, v127
	v_add_u32_e32 v128, 2, v130
	v_and_b32_e32 v128, 3, v128
	v_lshlrev_b32_e32 v128, 4, v128
	v_lshl_add_u32 v128, v125, 6, v128
	v_add_u32_e32 v129, 3, v130
	v_and_b32_e32 v129, 3, v129
	v_lshlrev_b32_e32 v129, 4, v129
	v_lshl_add_u32 v129, v125, 6, v129
	v_and_b32_e32 v125, 3, v232
	s_sub_i32 s98, s24, s25
	s_movk_i32 s99, 0x1000
	s_cmp_eq_u32 s37, 0
	s_cselect_b32 s99, 0xffffff00, s99
	s_add_i32 s98, s98, s99
	s_lshl_b32 s98, s98, 9
	s_ashr_i32 s99, s98, 31
	v_mov_b32_e32 v120, s98
	v_mov_b32_e32 v121, s99
	s_lshl_b32 s98, s98, 1
	v_mov_b32_e32 v118, s98
	v_mov_b32_e32 v119, s99
	s_lshl_b32 s98, s98, 1
	v_mov_b32_e32 v110, s98
	v_mov_b32_e32 v111, s99
	v_lshlrev_b32_e32 v112, 15, v112
	v_ashrrev_i32_e32 v114, 1, v112
	v_mov_b32_e32 v115, v113
	v_ashrrev_i32_e32 v116, 2, v112
	v_mov_b32_e32 v117, v113
	s_mov_b32 s49, 0
	s_mov_b32 s51, 0
	s_branch .LBB0_1106

.LBB0_1149:
	s_add_i32 s2, s49, -1
	s_lshl_b32 s3, s2, 14
	s_and_b32 s3, s3, 0x4000
	v_add_u32_e32 v46, s3, v126
	v_add_u32_e32 v50, s3, v127
	v_add_u32_e32 v38, s3, v128
	v_add_u32_e32 v42, s3, v129
	ds_read_b128 v[46:49], v46 offset:43008
	ds_read_b128 v[50:53], v50 offset:43008
	ds_read_b128 v[38:41], v38 offset:43008
	ds_read_b128 v[42:45], v42 offset:43008

.LBB0_1209:
	s_lshl_b32 s2, s49, 14
	s_and_b32 s2, s2, 0x4000
	v_add_u32_e32 v46, s2, v126
	v_add_u32_e32 v50, s2, v127
	v_add_u32_e32 v38, s2, v128
	v_add_u32_e32 v42, s2, v129
	ds_read_b128 v[46:49], v46 offset:43008
	ds_read_b128 v[50:53], v50 offset:43008
	ds_read_b128 v[38:41], v38 offset:43008
	ds_read_b128 v[42:45], v42 offset:43008

.LBB0_1266:
	s_add_i32 s2, s49, 1
	s_lshl_b32 s3, s2, 14
	s_and_b32 s3, s3, 0x4000
	v_add_u32_e32 v46, s3, v126
	v_add_u32_e32 v50, s3, v127
	v_add_u32_e32 v38, s3, v128
	v_add_u32_e32 v42, s3, v129
	ds_read_b128 v[46:49], v46 offset:43008
	ds_read_b128 v[50:53], v50 offset:43008
	ds_read_b128 v[38:41], v38 offset:43008
	ds_read_b128 v[42:45], v42 offset:43008
	s_branch .LBB0_1104
.LBB0_1277:
	s_waitcnt vmcnt(6)
	ds_read_b128 v[2:5], v126 offset:59392
	s_waitcnt vmcnt(4)
	ds_read_b128 v[6:9], v127 offset:59392
	s_waitcnt vmcnt(3)
	ds_read_b128 v[10:13], v128 offset:59392
	ds_read_b128 v[14:17], v129 offset:59392
	s_or_b32 s2, s24, 15
	v_add_u32_e32 v0, s24, v55
	s_waitcnt lgkmcnt(2)
	v_pk_add_f32 v[4:5], v[4:5], v[8:9]
	v_pk_add_f32 v[2:3], v[2:3], v[6:7]
	s_waitcnt lgkmcnt(0)
	v_pk_add_f32 v[6:7], v[12:13], v[16:17]
	v_pk_add_f32 v[8:9], v[10:11], v[14:15]
	v_add_u32_e32 v0, 0xff0, v0
	v_sub_u32_e32 v18, s2, v55
	v_pk_add_f32 v[4:5], v[4:5], v[6:7]
	v_pk_add_f32 v[2:3], v[2:3], v[8:9]
	v_cndmask_b32_e64 v18, v18, v0, s[16:17]
	s_nop 1
	v_add_f32_dpp v2, v2, v2 quad_perm:[1,0,3,2] row_mask:0xf bank_mask:0xf bound_ctrl:1
	v_add_f32_dpp v3, v3, v3 quad_perm:[1,0,3,2] row_mask:0xf bank_mask:0xf bound_ctrl:1
	v_add_f32_dpp v4, v4, v4 quad_perm:[1,0,3,2] row_mask:0xf bank_mask:0xf bound_ctrl:1
	v_add_f32_dpp v5, v5, v5 quad_perm:[1,0,3,2] row_mask:0xf bank_mask:0xf bound_ctrl:1
	v_add_f32_dpp v2, v2, v2 quad_perm:[2,3,0,1] row_mask:0xf bank_mask:0xf bound_ctrl:1
	v_add_f32_dpp v3, v3, v3 quad_perm:[2,3,0,1] row_mask:0xf bank_mask:0xf bound_ctrl:1
	v_add_f32_dpp v4, v4, v4 quad_perm:[2,3,0,1] row_mask:0xf bank_mask:0xf bound_ctrl:1
	v_add_f32_dpp v5, v5, v5 quad_perm:[2,3,0,1] row_mask:0xf bank_mask:0xf bound_ctrl:1
	v_cmp_eq_u32_e64 s[2:3], 1, v125
	s_nop 1
	v_cndmask_b32_e64 v6, v2, v3, s[2:3]
	v_cmp_eq_u32_e64 s[2:3], 2, v125
	s_nop 1
	v_cndmask_b32_e64 v6, v6, v4, s[2:3]
	v_cmp_eq_u32_e64 s[2:3], 3, v125
	s_nop 1
	v_cndmask_b32_e64 v6, v6, v5, s[2:3]
	v_ashrrev_i32_e32 v19, 31, v18
	v_readlane_b32 s2, v252, 14
	v_lshlrev_b64 v[2:3], 11, v[18:19]
	v_readlane_b32 s3, v252, 15
	s_mov_b32 s49, s21
	s_mov_b32 s51, s21
	v_lshl_add_u64 v[2:3], s[2:3], 0, v[2:3]
	v_lshl_add_u64 v[2:3], v[2:3], 0, s[20:21]
	v_lshl_add_u64 v[2:3], v[2:3], 0, s[48:49]
	v_lshl_add_u64 v[2:3], v[2:3], 0, s[50:51]
	v_lshlrev_b32_e32 v0, 2, v54
	v_lshl_add_u64 v[2:3], v[2:3], 0, v[0:1]
	global_store_dword v[108:109], v6, off
	s_mov_b32 s20, 0x10000
